# y1 + DA loops: K-fragment LDS reads issued right after the tile barrier, next-tile global loads after them
# speedup vs baseline: 1.0076x; 1.0076x over previous
; template <int MODE> ...
;     ...
;     for (int kt = kt_lo; kt <= kt_hi; ++kt) {
;         const int bufsel = (kt - kt_lo) & 1;
;         __syncthreads();
;         const bool more = kt < kt_hi;
;         if (more) {
;             const int kv1 = 64 * (kt + 1);
;             kr0 = *(const GAS u32x4*)(ksrc + (tok0 + (size_t)(kv1 + kp_row0) * dil) * 2048);
;             kr1 = *(const GAS u32x4*)(ksrc + (tok0 + (size_t)(kv1 + kp_row0 + 32) * dil) * 2048);
;             vr0 = *(const GAS u32x4*)(vsrc + kv1);
;             vr1 = *(const GAS u32x4*)(vsrc + (size_t)64 * TOK + kv1);
;             asm volatile("" ::: "memory");
;         }
;         const int kv0 = 64 * kt;
;         bool skip = kv0 > q_lo + 31;
;         if (MODE == 1) skip = skip || (kv0 + 63 < q_lo - 128);
;         if (!skip) {
;             const LAS unsigned char* kb = lds + bufsel * AT_BUF; const LAS unsigned char* vb = kb + AT_KBYTES;
;             f32x16 s0, s1;
; #pragma unroll
;             for (int r = 0; r < 16; ++r) { s0[r] = 0.f; s1[r] = 0.f; }
;             {
;                 bf16x8 ka[4], kc[4];
; #pragma unroll
;                 for (int ds = 0; ds < 4; ++ds) {
;                     ka[ds] = *(const LAS bf16x8*)(kb + r32 * AT_KROW + mp * 128 + (16 * ds + 8 * hi) * 2);
;                     kc[ds] = *(const LAS bf16x8*)(kb + (32 + r32) * AT_KROW + mp * 128 + (16 * ds + 8 * hi) * 2);
;                 }
;                 __builtin_amdgcn_sched_barrier(0);
; #pragma unroll
;                 for (int ds = 0; ds < 4; ++ds) {
;                     s0 = __builtin_amdgcn_mfma_f32_32x32x16_bf16(ka[ds], qf[ds], s0, 0, 0, 0);
;                     s1 = __builtin_amdgcn_mfma_f32_32x32x16_bf16(kc[ds], qf[ds], s1, 0, 0, 0);
;                 }
;             }
;             const int relbase = qi - kv0 - 4 * hi;
;             constexpr int cmax = (MODE == 0) ? 2047 : 128;
;             float mx = -1e30f;
;             bool interior = (kv0 + 63 <= q_lo);
;             if (MODE == 1) interior = interior && (q_lo + 31 - kv0 <= 128);
;             if (interior) {
;                 const LAS float* p = biasL + mp * 2048 + (relbase - 59);
; #pragma unroll
;                 for (int r = 0; r < 16; ++r) {
;                     const int o = 59 - ((r & 3) + 8 * (r >> 2));
;                     s0[r] += p[o]; s1[r] += p[o - 32];
;                     mx = fmaxf(mx, fmaxf(s0[r], s1[r]));
;                 }
.LBB0_381:
	v_lshl_add_u64 v[2:3], s[54:55], 0, v[144:145]
	v_add_co_u32_e32 v4, vcc, s90, v2
	v_lshl_add_u64 v[10:11], s[54:55], 0, v[142:143]
	s_nop 0
	v_addc_co_u32_e32 v5, vcc, 0, v3, vcc
	v_add_co_u32_e32 v6, vcc, s91, v2
	s_waitcnt lgkmcnt(0)
	s_nop 0
	v_addc_co_u32_e32 v7, vcc, 0, v3, vcc
	v_add_co_u32_e32 v12, vcc, 0x20000000, v10
	s_barrier
	s_and_b32 s29, s25, 1
	s_add_i32 s28, s14, 64
	s_cmp_gt_u32 s28, s26
	s_cbranch_scc1 .Lkh_skip_A
	s_mul_i32 s15, s29, 0x8800
	s_add_i32 s30, s15, 0
	s_add_i32 s15, s27, s30
	v_add3_u32 v0, s15, v197, v136
	ds_read_b128 v[80:83], v0
	ds_read_b128 v[148:151], v0 offset:32
	ds_read_b128 v[84:87], v0 offset:8704
	ds_read_b128 v[152:155], v0 offset:8736
	ds_read_b128 v[156:159], v0 offset:64
	ds_read_b128 v[160:163], v0 offset:96
	ds_read_b128 v[164:167], v0 offset:8768
	ds_read_b128 v[168:171], v0 offset:8800
	s_nop 0
	v_addc_co_u32_e32 v13, vcc, 0, v11, vcc
	v_add_co_u32_e32 v14, vcc, 0x20800000, v10
	global_load_dwordx4 v[2:5], v[4:5], off offset:2048
	s_nop 0
	global_load_dwordx4 v[6:9], v[6:7], off offset:2048
	v_addc_co_u32_e32 v15, vcc, 0, v11, vcc
	global_load_dwordx4 v[10:13], v[12:13], off offset:128
	s_nop 0
	global_load_dwordx4 v[128:131], v[14:15], off offset:128
	ds_read2_b32 v[14:15], v200 offset0:59 offset1:58
	ds_read2_b32 v[218:219], v200 offset0:27 offset1:26
	ds_read2_b32 v[220:221], v200 offset0:25 offset1:24
	ds_read2_b32 v[222:223], v200 offset0:57 offset1:56
	ds_read2_b32 v[224:225], v200 offset0:51 offset1:50
	ds_read2_b32 v[174:175], v200 offset0:19 offset1:18
	ds_read2_b32 v[226:227], v200 offset0:49 offset1:48
	s_waitcnt lgkmcnt(14)
	v_mfma_f32_32x32x16_bf16 v[96:111], v[80:83], v[124:127], 0
	s_add_i32 s31, s14, 0x7f
	s_mov_b64 s[14:15], -1
	s_cmp_gt_u32 s31, s24
	ds_read2_b32 v[172:173], v200 offset0:17 offset1:16
	s_waitcnt lgkmcnt(13)
	v_mfma_f32_32x32x16_bf16 v[80:95], v[84:87], v[124:127], 0
	v_mfma_f32_32x32x16_bf16 v[96:111], v[148:151], v[120:123], v[96:111]
	ds_read2_b32 v[242:243], v200 offset0:43 offset1:42
	ds_read2_b32 v[182:183], v200 offset0:11 offset1:10
	s_waitcnt lgkmcnt(14)
	v_mfma_f32_32x32x16_bf16 v[80:95], v[152:155], v[120:123], v[80:95]
	ds_read2_b32 v[176:177], v200 offset0:41 offset1:40
	s_waitcnt lgkmcnt(14)
	v_mfma_f32_32x32x16_bf16 v[96:111], v[156:159], v[116:119], v[96:111]
	ds_read2_b32 v[184:185], v200 offset0:9 offset1:8
	s_waitcnt lgkmcnt(13)
	v_mfma_f32_32x32x16_bf16 v[80:95], v[164:167], v[116:119], v[80:95]
	v_mfma_f32_32x32x16_bf16 v[96:111], v[160:163], v[112:115], v[96:111]
	ds_read2_b32 v[180:181], v200 offset0:35 offset1:34
	ds_read2_b32 v[188:189], v200 offset0:3 offset1:2
	s_waitcnt lgkmcnt(14)
	v_mfma_f32_32x32x16_bf16 v[80:95], v[168:171], v[112:115], v[80:95]
	ds_read2_b32 v[178:179], v200 offset0:33 offset1:32
	s_nop 11
	s_cbranch_scc1 .LdaA_bias_masked
	s_waitcnt lgkmcnt(14)
	v_add_f32_e32 v14, v96, v14
	v_add_f32_e32 v15, v97, v15
	ds_read2_b32 v[186:187], v200 offset0:1 offset1:0
	s_waitcnt lgkmcnt(14)
	v_add_f32_e32 v166, v80, v218
	v_add_f32_e32 v167, v81, v219
	s_waitcnt lgkmcnt(13)
	v_add_f32_e32 v168, v82, v220
	v_add_f32_e32 v169, v83, v221
	s_waitcnt lgkmcnt(12)
	v_add_f32_e32 v148, v98, v222
	v_add_f32_e32 v149, v99, v223
	s_waitcnt lgkmcnt(11)
	v_add_f32_e32 v152, v100, v224
	v_add_f32_e32 v153, v101, v225
	s_waitcnt lgkmcnt(10)
	v_add_f32_e32 v174, v84, v174
	v_add_f32_e32 v175, v85, v175
	s_waitcnt lgkmcnt(9)
	v_add_f32_e32 v150, v102, v226
	v_add_f32_e32 v151, v103, v227
	s_waitcnt lgkmcnt(8)
	v_add_f32_e32 v172, v86, v172
	v_add_f32_e32 v173, v87, v173
	s_waitcnt lgkmcnt(7)
	v_add_f32_e32 v170, v104, v242
	v_add_f32_e32 v171, v105, v243
	s_waitcnt lgkmcnt(6)
	v_add_f32_e32 v182, v88, v182
	v_add_f32_e32 v183, v89, v183
	s_waitcnt lgkmcnt(5)
	v_add_f32_e32 v176, v106, v176
	v_add_f32_e32 v177, v107, v177
	s_waitcnt lgkmcnt(4)
	v_add_f32_e32 v184, v90, v184
	v_add_f32_e32 v185, v91, v185
	s_waitcnt lgkmcnt(3)
	v_add_f32_e32 v180, v108, v180
	v_add_f32_e32 v181, v109, v181
	s_waitcnt lgkmcnt(2)
	v_add_f32_e32 v188, v92, v188
	v_add_f32_e32 v189, v93, v189
	s_waitcnt lgkmcnt(1)
	v_add_f32_e32 v178, v110, v178
	v_add_f32_e32 v179, v111, v179
	s_waitcnt lgkmcnt(0)
	v_add_f32_e32 v186, v94, v186
	v_add_f32_e32 v187, v95, v187
	v_max_f32_e32 v80, v14, v166
	v_max_f32_e32 v81, v15, v167
	v_max3_f32 v82, v80, s84, v81
	v_max_f32_e32 v80, v168, v148
	v_max_f32_e32 v81, v169, v149
	v_max3_f32 v82, v82, v80, v81
	v_max_f32_e32 v80, v152, v174
	v_max_f32_e32 v81, v153, v175
	v_max3_f32 v82, v82, v80, v81
	v_max_f32_e32 v80, v150, v172
	v_max_f32_e32 v81, v151, v173
	v_max3_f32 v82, v82, v80, v81
	v_max_f32_e32 v80, v170, v182
	v_max_f32_e32 v81, v171, v183
	v_max3_f32 v82, v82, v80, v81
	v_max_f32_e32 v80, v176, v184
	v_max_f32_e32 v81, v177, v185
	v_max3_f32 v82, v82, v80, v81
	v_max_f32_e32 v80, v180, v188
	v_max_f32_e32 v81, v181, v189
	v_max3_f32 v82, v82, v80, v81
	v_max_f32_e32 v80, v178, v186
	v_max_f32_e32 v81, v179, v187
	v_max3_f32 v0, v82, v80, v81
	s_branch .LBB0_386

; #define GAS __attribute__((address_space(1)))
; template <int MODE> ...
;     ...
;         const bool more = kt < kt_hi;
;         if (more) {
;             const int kv1 = 64 * (kt + 1);
;             kr0 = *(const GAS u32x4*)(ksrc + (tok0 + (size_t)(kv1 + kp_row0) * dil) * 2048);
;             kr1 = *(const GAS u32x4*)(ksrc + (tok0 + (size_t)(kv1 + kp_row0 + 32) * dil) * 2048);
;             vr0 = *(const GAS u32x4*)(vsrc + kv1);
;             vr1 = *(const GAS u32x4*)(vsrc + (size_t)64 * TOK + kv1);
;             asm volatile("" ::: "memory");
;         }
.Lkh_skip_A:
	s_nop 0
	v_addc_co_u32_e32 v13, vcc, 0, v11, vcc
	v_add_co_u32_e32 v14, vcc, 0x20800000, v10
	global_load_dwordx4 v[2:5], v[4:5], off offset:2048
	s_nop 0
	global_load_dwordx4 v[6:9], v[6:7], off offset:2048
	v_addc_co_u32_e32 v15, vcc, 0, v11, vcc
	global_load_dwordx4 v[10:13], v[12:13], off offset:128
	s_nop 0
	global_load_dwordx4 v[128:131], v[14:15], off offset:128
	s_branch .LBB0_387

; template <int MODE> ...
;     ...
;     for (int kt = kt_lo; kt <= kt_hi; ++kt) {
;         const int bufsel = (kt - kt_lo) & 1;
;         __syncthreads();
;         const bool more = kt < kt_hi;
;         if (more) {
;             const int kv1 = 64 * (kt + 1);
;             kr0 = *(const GAS u32x4*)(ksrc + (tok0 + (size_t)(kv1 + kp_row0) * dil) * 2048);
;             kr1 = *(const GAS u32x4*)(ksrc + (tok0 + (size_t)(kv1 + kp_row0 + 32) * dil) * 2048);
;             vr0 = *(const GAS u32x4*)(vsrc + kv1);
;             vr1 = *(const GAS u32x4*)(vsrc + (size_t)64 * TOK + kv1);
;             asm volatile("" ::: "memory");
;         }
;         const int kv0 = 64 * kt;
;         bool skip = kv0 > q_lo + 31;
;         if (MODE == 1) skip = skip || (kv0 + 63 < q_lo - 128);
;         if (!skip) {
;             const LAS unsigned char* kb = lds + bufsel * AT_BUF; const LAS unsigned char* vb = kb + AT_KBYTES;
;             f32x16 s0, s1;
; #pragma unroll
;             for (int r = 0; r < 16; ++r) { s0[r] = 0.f; s1[r] = 0.f; }
;             {
;                 bf16x8 ka[4], kc[4];
; #pragma unroll
;                 for (int ds = 0; ds < 4; ++ds) {
;                     ka[ds] = *(const LAS bf16x8*)(kb + r32 * AT_KROW + mp * 128 + (16 * ds + 8 * hi) * 2);
;                     kc[ds] = *(const LAS bf16x8*)(kb + (32 + r32) * AT_KROW + mp * 128 + (16 * ds + 8 * hi) * 2);
;                 }
;                 __builtin_amdgcn_sched_barrier(0);
; #pragma unroll
;                 for (int ds = 0; ds < 4; ++ds) {
;                     s0 = __builtin_amdgcn_mfma_f32_32x32x16_bf16(ka[ds], qf[ds], s0, 0, 0, 0);
;                     s1 = __builtin_amdgcn_mfma_f32_32x32x16_bf16(kc[ds], qf[ds], s1, 0, 0, 0);
;                 }
;             }
;             const int relbase = qi - kv0 - 4 * hi;
;             constexpr int cmax = (MODE == 0) ? 2047 : 128;
;             float mx = -1e30f;
;             bool interior = (kv0 + 63 <= q_lo);
;             if (MODE == 1) interior = interior && (q_lo + 31 - kv0 <= 128);
;             if (interior) {
;                 const LAS float* p = biasL + mp * 2048 + (relbase - 59);
; #pragma unroll
;                 for (int r = 0; r < 16; ++r) {
;                     const int o = 59 - ((r & 3) + 8 * (r >> 2));
;                     s0[r] += p[o]; s1[r] += p[o - 32];
;                     mx = fmaxf(mx, fmaxf(s0[r], s1[r]));
;                 }
.LBB0_402:
	v_lshl_add_u64 v[2:3], s[54:55], 0, v[144:145]
	v_add_co_u32_e32 v4, vcc, s90, v2
	v_lshl_add_u64 v[10:11], s[54:55], 0, v[142:143]
	s_nop 0
	v_addc_co_u32_e32 v5, vcc, 0, v3, vcc
	v_add_co_u32_e32 v6, vcc, s91, v2
	s_waitcnt lgkmcnt(0)
	s_nop 0
	v_addc_co_u32_e32 v7, vcc, 0, v3, vcc
	v_add_co_u32_e32 v12, vcc, 0x20000000, v10
	s_barrier
	s_and_b32 s9, s19, 1
	s_add_i32 s8, s0, 64
	s_cmp_gt_u32 s8, s21
	s_cbranch_scc1 .Lkh_skip_B
	s_mul_i32 s1, s9, 0x8800
	s_add_i32 s12, s1, 0
	s_add_i32 s1, s20, s12
	v_add3_u32 v0, s1, v197, v140
	ds_read_b128 v[80:83], v0
	ds_read_b128 v[148:151], v0 offset:32
	ds_read_b128 v[84:87], v0 offset:8704
	ds_read_b128 v[152:155], v0 offset:8736
	ds_read_b128 v[156:159], v0 offset:64
	ds_read_b128 v[160:163], v0 offset:96
	ds_read_b128 v[164:167], v0 offset:8768
	ds_read_b128 v[168:171], v0 offset:8800
	s_nop 0
	v_addc_co_u32_e32 v13, vcc, 0, v11, vcc
	v_add_co_u32_e32 v14, vcc, 0x20800000, v10
	global_load_dwordx4 v[2:5], v[4:5], off offset:2048
	s_nop 0
	global_load_dwordx4 v[6:9], v[6:7], off offset:2048
	v_addc_co_u32_e32 v15, vcc, 0, v11, vcc
	global_load_dwordx4 v[10:13], v[12:13], off offset:128
	s_nop 0
	global_load_dwordx4 v[128:131], v[14:15], off offset:128
	ds_read2_b32 v[14:15], v202 offset0:59 offset1:58
	ds_read2_b32 v[218:219], v202 offset0:27 offset1:26
	ds_read2_b32 v[220:221], v202 offset0:57 offset1:56
	ds_read2_b32 v[222:223], v202 offset0:25 offset1:24
	ds_read2_b32 v[224:225], v202 offset0:51 offset1:50
	ds_read2_b32 v[174:175], v202 offset0:19 offset1:18
	ds_read2_b32 v[226:227], v202 offset0:49 offset1:48
	s_waitcnt lgkmcnt(14)
	s_waitcnt vmcnt(7)
	v_mfma_f32_32x32x16_bf16 v[96:111], v[80:83], v[124:127], 0
	s_add_i32 s13, s0, 0x7f
	s_mov_b64 s[0:1], -1
	s_cmp_gt_u32 s13, s15
	ds_read2_b32 v[172:173], v202 offset0:17 offset1:16
	s_waitcnt lgkmcnt(13)
	v_mfma_f32_32x32x16_bf16 v[80:95], v[84:87], v[124:127], 0
	s_waitcnt vmcnt(6)
	v_mfma_f32_32x32x16_bf16 v[96:111], v[148:151], v[120:123], v[96:111]
	ds_read2_b32 v[242:243], v202 offset0:43 offset1:42
	ds_read2_b32 v[182:183], v202 offset0:11 offset1:10
	s_waitcnt lgkmcnt(14)
	v_mfma_f32_32x32x16_bf16 v[80:95], v[152:155], v[120:123], v[80:95]
	ds_read2_b32 v[176:177], v202 offset0:41 offset1:40
	s_waitcnt lgkmcnt(14)
	s_waitcnt vmcnt(5)
	v_mfma_f32_32x32x16_bf16 v[96:111], v[156:159], v[116:119], v[96:111]
	ds_read2_b32 v[184:185], v202 offset0:9 offset1:8
	s_waitcnt lgkmcnt(13)
	v_mfma_f32_32x32x16_bf16 v[80:95], v[164:167], v[116:119], v[80:95]
	s_waitcnt vmcnt(4)
	v_mfma_f32_32x32x16_bf16 v[96:111], v[160:163], v[112:115], v[96:111]
	ds_read2_b32 v[180:181], v202 offset0:35 offset1:34
	ds_read2_b32 v[188:189], v202 offset0:3 offset1:2
	s_waitcnt lgkmcnt(14)
	v_mfma_f32_32x32x16_bf16 v[80:95], v[168:171], v[112:115], v[80:95]
	ds_read2_b32 v[178:179], v202 offset0:33 offset1:32
	s_nop 11
	s_cbranch_scc1 .LdaB_bias_masked
	s_waitcnt lgkmcnt(14)
	v_add_f32_e32 v14, v96, v14
	v_add_f32_e32 v15, v97, v15
	ds_read2_b32 v[186:187], v202 offset0:1 offset1:0
	s_waitcnt lgkmcnt(14)
	v_add_f32_e32 v166, v80, v218
	v_add_f32_e32 v167, v81, v219
	s_waitcnt lgkmcnt(13)
	v_add_f32_e32 v148, v98, v220
	v_add_f32_e32 v149, v99, v221
	s_waitcnt lgkmcnt(12)
	v_add_f32_e32 v168, v82, v222
	v_add_f32_e32 v169, v83, v223
	s_waitcnt lgkmcnt(11)
	v_add_f32_e32 v152, v100, v224
	v_add_f32_e32 v153, v101, v225
	s_waitcnt lgkmcnt(10)
	v_add_f32_e32 v174, v84, v174
	v_add_f32_e32 v175, v85, v175
	s_waitcnt lgkmcnt(9)
	v_add_f32_e32 v150, v102, v226
	v_add_f32_e32 v151, v103, v227
	s_waitcnt lgkmcnt(8)
	v_add_f32_e32 v172, v86, v172
	v_add_f32_e32 v173, v87, v173
	s_waitcnt lgkmcnt(7)
	v_add_f32_e32 v170, v104, v242
	v_add_f32_e32 v171, v105, v243
	s_waitcnt lgkmcnt(6)
	v_add_f32_e32 v182, v88, v182
	v_add_f32_e32 v183, v89, v183
	s_waitcnt lgkmcnt(5)
	v_add_f32_e32 v176, v106, v176
	v_add_f32_e32 v177, v107, v177
	s_waitcnt lgkmcnt(4)
	v_add_f32_e32 v184, v90, v184
	v_add_f32_e32 v185, v91, v185
	s_waitcnt lgkmcnt(3)
	v_add_f32_e32 v180, v108, v180
	v_add_f32_e32 v181, v109, v181
	s_waitcnt lgkmcnt(2)
	v_add_f32_e32 v188, v92, v188
	v_add_f32_e32 v189, v93, v189
	s_waitcnt lgkmcnt(1)
	v_add_f32_e32 v178, v110, v178
	v_add_f32_e32 v179, v111, v179
	s_waitcnt lgkmcnt(0)
	v_add_f32_e32 v186, v94, v186
	v_add_f32_e32 v187, v95, v187
	v_max_f32_e32 v80, v14, v166
	v_max_f32_e32 v81, v15, v167
	v_max3_f32 v82, v80, s84, v81
	v_max_f32_e32 v80, v148, v168
	v_max_f32_e32 v81, v149, v169
	v_max3_f32 v82, v82, v80, v81
	v_max_f32_e32 v80, v152, v174
	v_max_f32_e32 v81, v153, v175
	v_max3_f32 v82, v82, v80, v81
	v_max_f32_e32 v80, v150, v172
	v_max_f32_e32 v81, v151, v173
	v_max3_f32 v82, v82, v80, v81
	v_max_f32_e32 v80, v170, v182
	v_max_f32_e32 v81, v171, v183
	v_max3_f32 v82, v82, v80, v81
	v_max_f32_e32 v80, v176, v184
	v_max_f32_e32 v81, v177, v185
	v_max3_f32 v82, v82, v80, v81
	v_max_f32_e32 v80, v180, v188
	v_max_f32_e32 v81, v181, v189
	v_max3_f32 v82, v82, v80, v81
	v_max_f32_e32 v80, v178, v186
	v_max_f32_e32 v81, v179, v187
	v_max3_f32 v0, v82, v80, v81
	s_branch .LBB0_407
